# cmp2 inner loops: bf16 weights read with ds_read_u16_d16_hi into zero-low-half registers (no shifts), packed FMAs take (z0,z1)x(w0,w1) directly; same products and per-accumulator order
# baseline (speedup 1.0000x reference)
.LBB0_606:
	s_waitcnt vmcnt(10)
	v_add_f32_e32 v7, v44, v46
	s_waitcnt vmcnt(3)
	v_add_f32_e32 v7, v7, v50
	v_add_f32_e32 v44, v45, v47
	v_mul_f32_e32 v45, 0xbfb8aa3b, v7
	v_exp_f32_e32 v45, v45
	v_add_f32_e32 v29, v29, v30
	s_waitcnt vmcnt(2)
	v_add_f32_e32 v44, v44, v49
	v_add_f32_e32 v25, v28, v25
	v_add_f32_e32 v30, 1.0, v45
	v_rcp_f32_e32 v30, v30
	s_waitcnt vmcnt(1)
	v_add_f32_e32 v29, v29, v48
	v_mul_f32_e32 v45, 0xbfb8aa3b, v44
	s_waitcnt vmcnt(0)
	v_add_f32_e32 v25, v25, v31
	v_exp_f32_e32 v45, v45
	v_mul_f32_e32 v7, v7, v30
	v_mul_f32_e32 v30, 0xbfb8aa3b, v29
	v_mul_f32_e32 v31, 0xbfb8aa3b, v25
	v_exp_f32_e32 v30, v30
	v_exp_f32_e32 v31, v31
	v_add_f32_e32 v28, 1.0, v45
	v_rcp_f32_e32 v28, v28
	v_add_f32_e32 v30, 1.0, v30
	v_add_f32_e32 v31, 1.0, v31
	v_rcp_f32_e32 v30, v30
	v_rcp_f32_e32 v31, v31
	v_mul_f32_e32 v28, v44, v28
	ds_write2st64_b32 v34, v7, v28 offset1:1
	v_mul_f32_e32 v7, v29, v30
	v_mul_f32_e32 v25, v25, v31
	ds_write2st64_b32 v34, v7, v25 offset0:2 offset1:3
	s_waitcnt lgkmcnt(0)
	v_lshlrev_b32_e32 v2, 1, v38
	v_mov_b32_e32 v28, 0
	v_and_or_b32 v2, v2, s29, v37
	s_mov_b32 s10, -4
	v_mov_b32_e32 v7, v33
	v_mov_b32_e32 v29, v28
	v_mov_b32_e32 v30, v28
	v_mov_b32_e32 v31, v28
	v_mov_b32_e32 v112, 0
	v_mov_b32_e32 v113, 0
	v_mov_b32_e32 v114, 0
	v_mov_b32_e32 v115, 0
	v_mov_b32_e32 v116, 0
	v_mov_b32_e32 v117, 0
	v_mov_b32_e32 v118, 0
	v_mov_b32_e32 v119, 0
	v_mov_b32_e32 v120, 0
	v_mov_b32_e32 v121, 0
	v_mov_b32_e32 v122, 0
	v_mov_b32_e32 v123, 0
	v_mov_b32_e32 v124, 0
	v_mov_b32_e32 v125, 0
	v_mov_b32_e32 v126, 0
	v_mov_b32_e32 v127, 0
	v_mov_b32_e32 v128, 0
	v_mov_b32_e32 v129, 0
	v_mov_b32_e32 v130, 0
	v_mov_b32_e32 v131, 0
	v_mov_b32_e32 v132, 0
	v_mov_b32_e32 v133, 0
	v_mov_b32_e32 v134, 0
	v_mov_b32_e32 v135, 0
	v_mov_b32_e32 v136, 0
	v_mov_b32_e32 v137, 0
	v_mov_b32_e32 v138, 0
	v_mov_b32_e32 v139, 0
	v_mov_b32_e32 v140, 0
	v_mov_b32_e32 v141, 0
	v_mov_b32_e32 v142, 0
	v_mov_b32_e32 v143, 0
.LBB0_607:
	v_add_u32_e32 v176, 0x10000, v7
	ds_read_b128 v[144:147], v176
	ds_read_b128 v[148:151], v176 offset:16
	ds_read_b128 v[152:155], v176 offset:32
	ds_read_b128 v[156:159], v176 offset:48
	ds_read_b128 v[160:163], v176 offset:64
	ds_read_b128 v[164:167], v176 offset:80
	ds_read_b128 v[168:171], v176 offset:96
	ds_read_b128 v[172:175], v176 offset:112
	ds_read_u16_d16_hi v112, v2
	ds_read_u16_d16_hi v113, v2 offset:128
	ds_read_u16_d16_hi v114, v2 offset:256
	ds_read_u16_d16_hi v115, v2 offset:384
	ds_read_u16_d16_hi v116, v2 offset:512
	ds_read_u16_d16_hi v117, v2 offset:640
	ds_read_u16_d16_hi v118, v2 offset:768
	ds_read_u16_d16_hi v119, v2 offset:896
	ds_read_u16_d16_hi v120, v2 offset:1024
	ds_read_u16_d16_hi v121, v2 offset:1152
	ds_read_u16_d16_hi v122, v2 offset:1280
	ds_read_u16_d16_hi v123, v2 offset:1408
	ds_read_u16_d16_hi v124, v2 offset:1536
	ds_read_u16_d16_hi v125, v2 offset:1664
	ds_read_u16_d16_hi v126, v2 offset:1792
	ds_read_u16_d16_hi v127, v2 offset:1920
	ds_read_u16_d16_hi v128, v2 offset:2048
	ds_read_u16_d16_hi v129, v2 offset:2176
	ds_read_u16_d16_hi v130, v2 offset:2304
	ds_read_u16_d16_hi v131, v2 offset:2432
	ds_read_u16_d16_hi v132, v2 offset:2560
	ds_read_u16_d16_hi v133, v2 offset:2688
	ds_read_u16_d16_hi v134, v2 offset:2816
	ds_read_u16_d16_hi v135, v2 offset:2944
	ds_read_u16_d16_hi v136, v2 offset:3072
	ds_read_u16_d16_hi v137, v2 offset:3200
	ds_read_u16_d16_hi v138, v2 offset:3328
	ds_read_u16_d16_hi v139, v2 offset:3456
	ds_read_u16_d16_hi v140, v2 offset:3584
	ds_read_u16_d16_hi v141, v2 offset:3712
	ds_read_u16_d16_hi v142, v2 offset:3840
	ds_read_u16_d16_hi v143, v2 offset:3968
	s_add_i32 s10, s10, 32
	s_waitcnt lgkmcnt(15)
	v_pk_fma_f32 v[28:29], v[144:145], v[112:113], v[28:29]
	v_pk_fma_f32 v[30:31], v[146:147], v[114:115], v[30:31]
	s_waitcnt lgkmcnt(15)
	v_pk_fma_f32 v[28:29], v[148:149], v[116:117], v[28:29]
	v_pk_fma_f32 v[30:31], v[150:151], v[118:119], v[30:31]
	s_waitcnt lgkmcnt(15)
	v_pk_fma_f32 v[28:29], v[152:153], v[120:121], v[28:29]
	v_pk_fma_f32 v[30:31], v[154:155], v[122:123], v[30:31]
	s_waitcnt lgkmcnt(15)
	v_pk_fma_f32 v[28:29], v[156:157], v[124:125], v[28:29]
	v_pk_fma_f32 v[30:31], v[158:159], v[126:127], v[30:31]
	s_waitcnt lgkmcnt(12)
	v_pk_fma_f32 v[28:29], v[160:161], v[128:129], v[28:29]
	v_pk_fma_f32 v[30:31], v[162:163], v[130:131], v[30:31]
	s_waitcnt lgkmcnt(8)
	v_pk_fma_f32 v[28:29], v[164:165], v[132:133], v[28:29]
	v_pk_fma_f32 v[30:31], v[166:167], v[134:135], v[30:31]
	s_waitcnt lgkmcnt(4)
	v_pk_fma_f32 v[28:29], v[168:169], v[136:137], v[28:29]
	v_pk_fma_f32 v[30:31], v[170:171], v[138:139], v[30:31]
	s_waitcnt lgkmcnt(0)
	v_pk_fma_f32 v[28:29], v[172:173], v[140:141], v[28:29]
	v_pk_fma_f32 v[30:31], v[174:175], v[142:143], v[30:31]
	v_add_u32_e32 v2, 0x1000, v2
	v_add_u32_e32 v7, 0x80, v7
	s_cmpk_gt_u32 s10, 0xfb
	s_cbranch_scc0 .LBB0_607
	v_add_f32_e32 v28, v28, v29
	v_add_f32_e32 v30, v30, v31
	v_add_f32_e32 v2, v28, v30
	v_cvt_pk_bf16_f32 v7, v2, s0
	v_lshlrev_b32_e32 v2, 1, v0
	v_lshl_add_u64 v[26:27], v[26:27], 0, v[2:3]
	global_store_short v[26:27], v7, off
	s_waitcnt lgkmcnt(0)
	s_andn2_saveexec_b64 s[8:9], s[8:9]
	s_cbranch_execz .LBB0_605

.LBB0_610:
	s_waitcnt vmcnt(5)
	v_ashrrev_i32_e32 v25, 31, v24
	v_lshlrev_b64 v[24:25], 7, v[24:25]
	v_lshl_add_u64 v[24:25], s[90:91], 0, v[24:25]
	v_cmp_ne_u32_e64 s[6:7], s26, v23
	s_and_saveexec_b64 s[10:11], s[6:7]
	s_xor_b64 s[6:7], exec, s[10:11]
	s_cbranch_execz .LBB0_614
	v_mul_f32_e32 v2, 0xbfb8aa3b, v17
	v_exp_f32_e32 v2, v2
	v_mul_f32_e32 v23, 0xbfb8aa3b, v16
	v_exp_f32_e32 v23, v23
	v_lshlrev_b32_e32 v7, 1, v39
	v_add_f32_e32 v2, 1.0, v2
	v_rcp_f32_e32 v26, v2
	v_mul_f32_e32 v27, 0xbfb8aa3b, v19
	v_and_or_b32 v2, v7, s29, v37
	v_add_f32_e32 v7, 1.0, v23
	v_mul_f32_e32 v23, v17, v26
	v_exp_f32_e32 v26, v27
	v_mul_f32_e32 v27, 0xbfb8aa3b, v18
	v_exp_f32_e32 v27, v27
	v_rcp_f32_e32 v7, v7
	v_add_f32_e32 v26, 1.0, v26
	v_rcp_f32_e32 v26, v26
	v_add_f32_e32 v27, 1.0, v27
	v_rcp_f32_e32 v27, v27
	v_mul_f32_e32 v7, v16, v7
	ds_write2st64_b32 v34, v23, v7 offset1:1
	v_mul_f32_e32 v7, v19, v26
	v_mul_f32_e32 v23, v18, v27
	ds_write2st64_b32 v34, v7, v23 offset0:2 offset1:3
	s_waitcnt lgkmcnt(0)
	v_mov_b32_e32 v26, 0
	s_mov_b32 s10, -4
	v_mov_b32_e32 v7, v33
	v_mov_b32_e32 v27, v26
	s_waitcnt vmcnt(4)
	v_mov_b32_e32 v28, v26
	v_mov_b32_e32 v29, v26
	v_mov_b32_e32 v112, 0
	v_mov_b32_e32 v113, 0
	v_mov_b32_e32 v114, 0
	v_mov_b32_e32 v115, 0
	v_mov_b32_e32 v116, 0
	v_mov_b32_e32 v117, 0
	v_mov_b32_e32 v118, 0
	v_mov_b32_e32 v119, 0
	v_mov_b32_e32 v120, 0
	v_mov_b32_e32 v121, 0
	v_mov_b32_e32 v122, 0
	v_mov_b32_e32 v123, 0
	v_mov_b32_e32 v124, 0
	v_mov_b32_e32 v125, 0
	v_mov_b32_e32 v126, 0
	v_mov_b32_e32 v127, 0
	v_mov_b32_e32 v128, 0
	v_mov_b32_e32 v129, 0
	v_mov_b32_e32 v130, 0
	v_mov_b32_e32 v131, 0
	v_mov_b32_e32 v132, 0
	v_mov_b32_e32 v133, 0
	v_mov_b32_e32 v134, 0
	v_mov_b32_e32 v135, 0
	v_mov_b32_e32 v136, 0
	v_mov_b32_e32 v137, 0
	v_mov_b32_e32 v138, 0
	v_mov_b32_e32 v139, 0
	v_mov_b32_e32 v140, 0
	v_mov_b32_e32 v141, 0
	v_mov_b32_e32 v142, 0
	v_mov_b32_e32 v143, 0
.LBB0_612:
	v_add_u32_e32 v176, 0x10000, v7
	ds_read_b128 v[144:147], v176
	ds_read_b128 v[148:151], v176 offset:16
	ds_read_b128 v[152:155], v176 offset:32
	ds_read_b128 v[156:159], v176 offset:48
	ds_read_b128 v[160:163], v176 offset:64
	ds_read_b128 v[164:167], v176 offset:80
	ds_read_b128 v[168:171], v176 offset:96
	ds_read_b128 v[172:175], v176 offset:112
	ds_read_u16_d16_hi v112, v2
	ds_read_u16_d16_hi v113, v2 offset:128
	ds_read_u16_d16_hi v114, v2 offset:256
	ds_read_u16_d16_hi v115, v2 offset:384
	ds_read_u16_d16_hi v116, v2 offset:512
	ds_read_u16_d16_hi v117, v2 offset:640
	ds_read_u16_d16_hi v118, v2 offset:768
	ds_read_u16_d16_hi v119, v2 offset:896
	ds_read_u16_d16_hi v120, v2 offset:1024
	ds_read_u16_d16_hi v121, v2 offset:1152
	ds_read_u16_d16_hi v122, v2 offset:1280
	ds_read_u16_d16_hi v123, v2 offset:1408
	ds_read_u16_d16_hi v124, v2 offset:1536
	ds_read_u16_d16_hi v125, v2 offset:1664
	ds_read_u16_d16_hi v126, v2 offset:1792
	ds_read_u16_d16_hi v127, v2 offset:1920
	ds_read_u16_d16_hi v128, v2 offset:2048
	ds_read_u16_d16_hi v129, v2 offset:2176
	ds_read_u16_d16_hi v130, v2 offset:2304
	ds_read_u16_d16_hi v131, v2 offset:2432
	ds_read_u16_d16_hi v132, v2 offset:2560
	ds_read_u16_d16_hi v133, v2 offset:2688
	ds_read_u16_d16_hi v134, v2 offset:2816
	ds_read_u16_d16_hi v135, v2 offset:2944
	ds_read_u16_d16_hi v136, v2 offset:3072
	ds_read_u16_d16_hi v137, v2 offset:3200
	ds_read_u16_d16_hi v138, v2 offset:3328
	ds_read_u16_d16_hi v139, v2 offset:3456
	ds_read_u16_d16_hi v140, v2 offset:3584
	ds_read_u16_d16_hi v141, v2 offset:3712
	ds_read_u16_d16_hi v142, v2 offset:3840
	ds_read_u16_d16_hi v143, v2 offset:3968
	s_add_i32 s10, s10, 32
	s_waitcnt lgkmcnt(15)
	v_pk_fma_f32 v[26:27], v[144:145], v[112:113], v[26:27]
	v_pk_fma_f32 v[28:29], v[146:147], v[114:115], v[28:29]
	s_waitcnt lgkmcnt(15)
	v_pk_fma_f32 v[26:27], v[148:149], v[116:117], v[26:27]
	v_pk_fma_f32 v[28:29], v[150:151], v[118:119], v[28:29]
	s_waitcnt lgkmcnt(15)
	v_pk_fma_f32 v[26:27], v[152:153], v[120:121], v[26:27]
	v_pk_fma_f32 v[28:29], v[154:155], v[122:123], v[28:29]
	s_waitcnt lgkmcnt(15)
	v_pk_fma_f32 v[26:27], v[156:157], v[124:125], v[26:27]
	v_pk_fma_f32 v[28:29], v[158:159], v[126:127], v[28:29]
	s_waitcnt lgkmcnt(12)
	v_pk_fma_f32 v[26:27], v[160:161], v[128:129], v[26:27]
	v_pk_fma_f32 v[28:29], v[162:163], v[130:131], v[28:29]
	s_waitcnt lgkmcnt(8)
	v_pk_fma_f32 v[26:27], v[164:165], v[132:133], v[26:27]
	v_pk_fma_f32 v[28:29], v[166:167], v[134:135], v[28:29]
	s_waitcnt lgkmcnt(4)
	v_pk_fma_f32 v[26:27], v[168:169], v[136:137], v[26:27]
	v_pk_fma_f32 v[28:29], v[170:171], v[138:139], v[28:29]
	s_waitcnt lgkmcnt(0)
	v_pk_fma_f32 v[26:27], v[172:173], v[140:141], v[26:27]
	v_pk_fma_f32 v[28:29], v[174:175], v[142:143], v[28:29]
	v_add_u32_e32 v2, 0x1000, v2
	v_add_u32_e32 v7, 0x80, v7
	s_cmpk_lt_u32 s10, 0xfc
	s_cbranch_scc1 .LBB0_612
	v_add_f32_e32 v26, v26, v27
	v_add_f32_e32 v28, v28, v29
	v_add_f32_e32 v2, v26, v28
	v_cvt_pk_bf16_f32 v7, v2, s0
	v_lshlrev_b32_e32 v2, 1, v0
	v_lshl_add_u64 v[24:25], v[24:25], 0, v[2:3]
	global_store_short v[24:25], v7, off
	s_waitcnt lgkmcnt(0)

.LBB0_616:
	s_or_b64 exec, exec, s[8:9]
	s_and_saveexec_b64 s[6:7], s[4:5]
	s_cbranch_execz .LBB0_623
	v_ashrrev_i32_e32 v23, 31, v22
	v_lshlrev_b64 v[22:23], 7, v[22:23]
	v_lshl_add_u64 v[22:23], s[90:91], 0, v[22:23]
	v_cmp_ne_u32_e64 s[4:5], s26, v21
	s_and_saveexec_b64 s[8:9], s[4:5]
	s_xor_b64 s[4:5], exec, s[8:9]
	s_cbranch_execz .LBB0_621
	v_mul_f32_e32 v2, 0xbfb8aa3b, v13
	v_exp_f32_e32 v2, v2
	v_mul_f32_e32 v21, 0xbfb8aa3b, v12
	v_exp_f32_e32 v21, v21
	v_lshlrev_b32_e32 v7, 1, v40
	v_add_f32_e32 v2, 1.0, v2
	v_rcp_f32_e32 v24, v2
	s_waitcnt vmcnt(5)
	v_mul_f32_e32 v25, 0xbfb8aa3b, v15
	v_and_or_b32 v2, v7, s29, v37
	v_add_f32_e32 v7, 1.0, v21
	v_mul_f32_e32 v21, v13, v24
	v_exp_f32_e32 v24, v25
	v_mul_f32_e32 v25, 0xbfb8aa3b, v14
	v_exp_f32_e32 v25, v25
	v_rcp_f32_e32 v7, v7
	v_add_f32_e32 v24, 1.0, v24
	v_rcp_f32_e32 v24, v24
	v_add_f32_e32 v25, 1.0, v25
	v_rcp_f32_e32 v25, v25
	v_mul_f32_e32 v7, v12, v7
	ds_write2st64_b32 v34, v21, v7 offset1:1
	v_mul_f32_e32 v7, v15, v24
	v_mul_f32_e32 v21, v14, v25
	ds_write2st64_b32 v34, v7, v21 offset0:2 offset1:3
	s_waitcnt lgkmcnt(0)
	v_mov_b32_e32 v24, 0
	s_mov_b32 s8, -4
	v_mov_b32_e32 v7, v33
	v_mov_b32_e32 v25, v24
	v_mov_b32_e32 v26, v24
	v_mov_b32_e32 v27, v24
	v_mov_b32_e32 v112, 0
	v_mov_b32_e32 v113, 0
	v_mov_b32_e32 v114, 0
	v_mov_b32_e32 v115, 0
	v_mov_b32_e32 v116, 0
	v_mov_b32_e32 v117, 0
	v_mov_b32_e32 v118, 0
	v_mov_b32_e32 v119, 0
	v_mov_b32_e32 v120, 0
	v_mov_b32_e32 v121, 0
	v_mov_b32_e32 v122, 0
	v_mov_b32_e32 v123, 0
	v_mov_b32_e32 v124, 0
	v_mov_b32_e32 v125, 0
	v_mov_b32_e32 v126, 0
	v_mov_b32_e32 v127, 0
	v_mov_b32_e32 v128, 0
	v_mov_b32_e32 v129, 0
	v_mov_b32_e32 v130, 0
	v_mov_b32_e32 v131, 0
	v_mov_b32_e32 v132, 0
	v_mov_b32_e32 v133, 0
	v_mov_b32_e32 v134, 0
	v_mov_b32_e32 v135, 0
	v_mov_b32_e32 v136, 0
	v_mov_b32_e32 v137, 0
	v_mov_b32_e32 v138, 0
	v_mov_b32_e32 v139, 0
	v_mov_b32_e32 v140, 0
	v_mov_b32_e32 v141, 0
	v_mov_b32_e32 v142, 0
	v_mov_b32_e32 v143, 0
.LBB0_619:
	v_add_u32_e32 v176, 0x10000, v7
	ds_read_b128 v[144:147], v176
	ds_read_b128 v[148:151], v176 offset:16
	ds_read_b128 v[152:155], v176 offset:32
	ds_read_b128 v[156:159], v176 offset:48
	ds_read_b128 v[160:163], v176 offset:64
	ds_read_b128 v[164:167], v176 offset:80
	ds_read_b128 v[168:171], v176 offset:96
	ds_read_b128 v[172:175], v176 offset:112
	ds_read_u16_d16_hi v112, v2
	ds_read_u16_d16_hi v113, v2 offset:128
	ds_read_u16_d16_hi v114, v2 offset:256
	ds_read_u16_d16_hi v115, v2 offset:384
	ds_read_u16_d16_hi v116, v2 offset:512
	ds_read_u16_d16_hi v117, v2 offset:640
	ds_read_u16_d16_hi v118, v2 offset:768
	ds_read_u16_d16_hi v119, v2 offset:896
	ds_read_u16_d16_hi v120, v2 offset:1024
	ds_read_u16_d16_hi v121, v2 offset:1152
	ds_read_u16_d16_hi v122, v2 offset:1280
	ds_read_u16_d16_hi v123, v2 offset:1408
	ds_read_u16_d16_hi v124, v2 offset:1536
	ds_read_u16_d16_hi v125, v2 offset:1664
	ds_read_u16_d16_hi v126, v2 offset:1792
	ds_read_u16_d16_hi v127, v2 offset:1920
	ds_read_u16_d16_hi v128, v2 offset:2048
	ds_read_u16_d16_hi v129, v2 offset:2176
	ds_read_u16_d16_hi v130, v2 offset:2304
	ds_read_u16_d16_hi v131, v2 offset:2432
	ds_read_u16_d16_hi v132, v2 offset:2560
	ds_read_u16_d16_hi v133, v2 offset:2688
	ds_read_u16_d16_hi v134, v2 offset:2816
	ds_read_u16_d16_hi v135, v2 offset:2944
	ds_read_u16_d16_hi v136, v2 offset:3072
	ds_read_u16_d16_hi v137, v2 offset:3200
	ds_read_u16_d16_hi v138, v2 offset:3328
	ds_read_u16_d16_hi v139, v2 offset:3456
	ds_read_u16_d16_hi v140, v2 offset:3584
	ds_read_u16_d16_hi v141, v2 offset:3712
	ds_read_u16_d16_hi v142, v2 offset:3840
	ds_read_u16_d16_hi v143, v2 offset:3968
	s_add_i32 s8, s8, 32
	s_waitcnt lgkmcnt(15)
	v_pk_fma_f32 v[24:25], v[144:145], v[112:113], v[24:25]
	v_pk_fma_f32 v[26:27], v[146:147], v[114:115], v[26:27]
	s_waitcnt lgkmcnt(15)
	v_pk_fma_f32 v[24:25], v[148:149], v[116:117], v[24:25]
	v_pk_fma_f32 v[26:27], v[150:151], v[118:119], v[26:27]
	s_waitcnt lgkmcnt(15)
	v_pk_fma_f32 v[24:25], v[152:153], v[120:121], v[24:25]
	v_pk_fma_f32 v[26:27], v[154:155], v[122:123], v[26:27]
	s_waitcnt lgkmcnt(15)
	v_pk_fma_f32 v[24:25], v[156:157], v[124:125], v[24:25]
	v_pk_fma_f32 v[26:27], v[158:159], v[126:127], v[26:27]
	s_waitcnt lgkmcnt(12)
	v_pk_fma_f32 v[24:25], v[160:161], v[128:129], v[24:25]
	v_pk_fma_f32 v[26:27], v[162:163], v[130:131], v[26:27]
	s_waitcnt lgkmcnt(8)
	v_pk_fma_f32 v[24:25], v[164:165], v[132:133], v[24:25]
	v_pk_fma_f32 v[26:27], v[166:167], v[134:135], v[26:27]
	s_waitcnt lgkmcnt(4)
	v_pk_fma_f32 v[24:25], v[168:169], v[136:137], v[24:25]
	v_pk_fma_f32 v[26:27], v[170:171], v[138:139], v[26:27]
	s_waitcnt lgkmcnt(0)
	v_pk_fma_f32 v[24:25], v[172:173], v[140:141], v[24:25]
	v_pk_fma_f32 v[26:27], v[174:175], v[142:143], v[26:27]
	v_add_u32_e32 v2, 0x1000, v2
	v_add_u32_e32 v7, 0x80, v7
	s_cmpk_lt_u32 s8, 0xfc
	s_cbranch_scc1 .LBB0_619
	v_add_f32_e32 v24, v24, v25
	v_add_f32_e32 v26, v26, v27
	v_add_f32_e32 v2, v24, v26
	v_cvt_pk_bf16_f32 v7, v2, s0
	v_lshlrev_b32_e32 v2, 1, v0
	v_lshl_add_u64 v[22:23], v[22:23], 0, v[2:3]
	global_store_short v[22:23], v7, off
	s_waitcnt lgkmcnt(0)

.LBB0_623:
	s_or_b64 exec, exec, s[6:7]
	s_and_saveexec_b64 s[4:5], s[2:3]
	s_cbranch_execz .LBB0_591
	v_ashrrev_i32_e32 v21, 31, v20
	v_lshlrev_b64 v[20:21], 7, v[20:21]
	v_lshl_add_u64 v[20:21], s[90:91], 0, v[20:21]
	v_cmp_ne_u32_e64 s[2:3], s26, v43
	s_and_saveexec_b64 s[6:7], s[2:3]
	s_xor_b64 s[2:3], exec, s[6:7]
	s_cbranch_execz .LBB0_628
	v_mul_f32_e32 v2, 0xbfb8aa3b, v9
	v_exp_f32_e32 v2, v2
	v_mul_f32_e32 v22, 0xbfb8aa3b, v8
	v_exp_f32_e32 v22, v22
	v_lshlrev_b32_e32 v7, 1, v41
	v_add_f32_e32 v2, 1.0, v2
	v_rcp_f32_e32 v23, v2
	v_mul_f32_e32 v24, 0xbfb8aa3b, v11
	v_and_or_b32 v2, v7, s29, v37
	v_add_f32_e32 v7, 1.0, v22
	v_mul_f32_e32 v22, v9, v23
	v_exp_f32_e32 v23, v24
	v_mul_f32_e32 v24, 0xbfb8aa3b, v10
	v_exp_f32_e32 v24, v24
	v_rcp_f32_e32 v7, v7
	v_add_f32_e32 v23, 1.0, v23
	v_rcp_f32_e32 v23, v23
	v_add_f32_e32 v24, 1.0, v24
	v_rcp_f32_e32 v24, v24
	v_mul_f32_e32 v7, v8, v7
	ds_write2st64_b32 v34, v22, v7 offset1:1
	v_mul_f32_e32 v7, v11, v23
	v_mul_f32_e32 v22, v10, v24
	ds_write2st64_b32 v34, v7, v22 offset0:2 offset1:3
	s_waitcnt lgkmcnt(0)
	v_mov_b32_e32 v22, 0
	s_mov_b32 s6, -4
	v_mov_b32_e32 v7, v33
	v_mov_b32_e32 v23, v22
	v_mov_b32_e32 v24, v22
	s_waitcnt vmcnt(5)
	v_mov_b32_e32 v25, v22
	v_mov_b32_e32 v112, 0
	v_mov_b32_e32 v113, 0
	v_mov_b32_e32 v114, 0
	v_mov_b32_e32 v115, 0
	v_mov_b32_e32 v116, 0
	v_mov_b32_e32 v117, 0
	v_mov_b32_e32 v118, 0
	v_mov_b32_e32 v119, 0
	v_mov_b32_e32 v120, 0
	v_mov_b32_e32 v121, 0
	v_mov_b32_e32 v122, 0
	v_mov_b32_e32 v123, 0
	v_mov_b32_e32 v124, 0
	v_mov_b32_e32 v125, 0
	v_mov_b32_e32 v126, 0
	v_mov_b32_e32 v127, 0
	v_mov_b32_e32 v128, 0
	v_mov_b32_e32 v129, 0
	v_mov_b32_e32 v130, 0
	v_mov_b32_e32 v131, 0
	v_mov_b32_e32 v132, 0
	v_mov_b32_e32 v133, 0
	v_mov_b32_e32 v134, 0
	v_mov_b32_e32 v135, 0
	v_mov_b32_e32 v136, 0
	v_mov_b32_e32 v137, 0
	v_mov_b32_e32 v138, 0
	v_mov_b32_e32 v139, 0
	v_mov_b32_e32 v140, 0
	v_mov_b32_e32 v141, 0
	v_mov_b32_e32 v142, 0
	v_mov_b32_e32 v143, 0
.LBB0_626:
	v_add_u32_e32 v176, 0x10000, v7
	ds_read_b128 v[144:147], v176
	ds_read_b128 v[148:151], v176 offset:16
	ds_read_b128 v[152:155], v176 offset:32
	ds_read_b128 v[156:159], v176 offset:48
	ds_read_b128 v[160:163], v176 offset:64
	ds_read_b128 v[164:167], v176 offset:80
	ds_read_b128 v[168:171], v176 offset:96
	ds_read_b128 v[172:175], v176 offset:112
	ds_read_u16_d16_hi v112, v2
	ds_read_u16_d16_hi v113, v2 offset:128
	ds_read_u16_d16_hi v114, v2 offset:256
	ds_read_u16_d16_hi v115, v2 offset:384
	ds_read_u16_d16_hi v116, v2 offset:512
	ds_read_u16_d16_hi v117, v2 offset:640
	ds_read_u16_d16_hi v118, v2 offset:768
	ds_read_u16_d16_hi v119, v2 offset:896
	ds_read_u16_d16_hi v120, v2 offset:1024
	ds_read_u16_d16_hi v121, v2 offset:1152
	ds_read_u16_d16_hi v122, v2 offset:1280
	ds_read_u16_d16_hi v123, v2 offset:1408
	ds_read_u16_d16_hi v124, v2 offset:1536
	ds_read_u16_d16_hi v125, v2 offset:1664
	ds_read_u16_d16_hi v126, v2 offset:1792
	ds_read_u16_d16_hi v127, v2 offset:1920
	ds_read_u16_d16_hi v128, v2 offset:2048
	ds_read_u16_d16_hi v129, v2 offset:2176
	ds_read_u16_d16_hi v130, v2 offset:2304
	ds_read_u16_d16_hi v131, v2 offset:2432
	ds_read_u16_d16_hi v132, v2 offset:2560
	ds_read_u16_d16_hi v133, v2 offset:2688
	ds_read_u16_d16_hi v134, v2 offset:2816
	ds_read_u16_d16_hi v135, v2 offset:2944
	ds_read_u16_d16_hi v136, v2 offset:3072
	ds_read_u16_d16_hi v137, v2 offset:3200
	ds_read_u16_d16_hi v138, v2 offset:3328
	ds_read_u16_d16_hi v139, v2 offset:3456
	ds_read_u16_d16_hi v140, v2 offset:3584
	ds_read_u16_d16_hi v141, v2 offset:3712
	ds_read_u16_d16_hi v142, v2 offset:3840
	ds_read_u16_d16_hi v143, v2 offset:3968
	s_add_i32 s6, s6, 32
	s_waitcnt lgkmcnt(15)
	v_pk_fma_f32 v[22:23], v[144:145], v[112:113], v[22:23]
	v_pk_fma_f32 v[24:25], v[146:147], v[114:115], v[24:25]
	s_waitcnt lgkmcnt(15)
	v_pk_fma_f32 v[22:23], v[148:149], v[116:117], v[22:23]
	v_pk_fma_f32 v[24:25], v[150:151], v[118:119], v[24:25]
	s_waitcnt lgkmcnt(15)
	v_pk_fma_f32 v[22:23], v[152:153], v[120:121], v[22:23]
	v_pk_fma_f32 v[24:25], v[154:155], v[122:123], v[24:25]
	s_waitcnt lgkmcnt(15)
	v_pk_fma_f32 v[22:23], v[156:157], v[124:125], v[22:23]
	v_pk_fma_f32 v[24:25], v[158:159], v[126:127], v[24:25]
	s_waitcnt lgkmcnt(12)
	v_pk_fma_f32 v[22:23], v[160:161], v[128:129], v[22:23]
	v_pk_fma_f32 v[24:25], v[162:163], v[130:131], v[24:25]
	s_waitcnt lgkmcnt(8)
	v_pk_fma_f32 v[22:23], v[164:165], v[132:133], v[22:23]
	v_pk_fma_f32 v[24:25], v[166:167], v[134:135], v[24:25]
	s_waitcnt lgkmcnt(4)
	v_pk_fma_f32 v[22:23], v[168:169], v[136:137], v[22:23]
	v_pk_fma_f32 v[24:25], v[170:171], v[138:139], v[24:25]
	s_waitcnt lgkmcnt(0)
	v_pk_fma_f32 v[22:23], v[172:173], v[140:141], v[22:23]
	v_pk_fma_f32 v[24:25], v[174:175], v[142:143], v[24:25]
	v_add_u32_e32 v2, 0x1000, v2
	v_add_u32_e32 v7, 0x80, v7
	s_cmpk_lt_u32 s6, 0xfc
	s_cbranch_scc1 .LBB0_626
	v_add_f32_e32 v22, v22, v23
	v_add_f32_e32 v24, v24, v25
	v_add_f32_e32 v2, v22, v24
	v_cvt_pk_bf16_f32 v7, v2, s0
	v_lshlrev_b32_e32 v2, 1, v0
	v_lshl_add_u64 v[20:21], v[20:21], 0, v[2:3]
	global_store_short v[20:21], v7, off
	s_waitcnt lgkmcnt(0)
